# K3: step-3 (KK^T/QK^T + decay masks) epilogue rewritten with wave-uniform scalar branching, per-lane base addresses and immediate offsets instead of per-element exec-masked branches
# speedup vs baseline: 1.0363x; 1.0158x over previous
.LBB0_194:
	s_or_b64 exec, exec, s[4:5]
	v_ashrrev_i32_e32 v82, 6, v186
	v_and_b32_e32 v190, 3, v82
	s_movk_i32 s0, 0x100
	v_lshlrev_b32_e32 v85, 4, v190
	v_and_b32_e32 v188, 31, v216
	v_cmp_gt_u32_e64 s[40:41], s0, v186
	v_and_b32_e32 v88, 32, v85
	v_lshrrev_b32_e32 v189, 5, v214
	v_cndmask_b32_e64 v0, v243, 0, s[40:41]
	v_or_b32_e32 v1, v88, v188
	v_mul_u32_u24_e32 v1, 0x110, v1
	v_lshlrev_b32_e32 v191, 4, v189
	v_add_u32_e32 v0, 0, v0
	v_lshlrev_b32_e32 v2, 5, v82
	v_add3_u32 v40, v0, v1, v191
	s_waitcnt lgkmcnt(0)
	s_barrier
	s_lshr_b32 s0, s87, 6
	s_bfe_u32 s1, s0, 0x10001
	s_and_b32 s2, s0, 1
	s_lshl_b32 s3, s2, 5
	v_add_u32_e32 v83, s3, v188
	v_mul_u32_u24_e32 v4, 0x110, v83
	v_add_u32_e32 v101, v4, v191
	v_mov_b32_e32 v100, v40
	ds_read_b128 v[16:19], v100
	ds_read_b128 v[20:23], v101
	ds_read_b128 v[24:27], v100 offset:32
	ds_read_b128 v[28:31], v101 offset:32
	ds_read_b128 v[32:35], v100 offset:64
	ds_read_b128 v[36:39], v101 offset:64
	ds_read_b128 v[40:43], v100 offset:96
	ds_read_b128 v[44:47], v101 offset:96
	ds_read_b128 v[48:51], v100 offset:128
	ds_read_b128 v[52:55], v101 offset:128
	ds_read_b128 v[56:59], v100 offset:160
	ds_read_b128 v[60:63], v101 offset:160
	ds_read_b128 v[64:67], v100 offset:192
	ds_read_b128 v[68:71], v101 offset:192
	ds_read_b128 v[72:75], v100 offset:224
	s_waitcnt lgkmcnt(14)
	ds_read_b128 v[76:79], v101 offset:224
	v_lshlrev_b32_e32 v86, 2, v83
	v_add_u32_e32 v86, 0x22c00, v86
	s_lshl_b32 s3, s1, 7
	v_lshl_add_u32 v87, v189, 4, s3
	v_add_u32_e32 v87, 0x22c00, v87
	s_sub_i32 s3, s2, s1
	s_lshl_b32 s3, s3, 5
	v_lshlrev_b32_e32 v99, 2, v189
	v_sub_u32_e32 v99, v188, v99
	v_add_u32_e32 v99, s3, v99
	s_waitcnt lgkmcnt(14)
	v_mfma_f32_32x32x16_bf16 v[0:15], v[16:19], v[20:23], 0
	s_waitcnt lgkmcnt(12)
	v_mfma_f32_32x32x16_bf16 v[0:15], v[24:27], v[28:31], v[0:15]
	s_waitcnt lgkmcnt(10)
	v_mfma_f32_32x32x16_bf16 v[0:15], v[32:35], v[36:39], v[0:15]
	s_waitcnt lgkmcnt(8)
	v_mfma_f32_32x32x16_bf16 v[0:15], v[40:43], v[44:47], v[0:15]
	s_waitcnt lgkmcnt(6)
	v_mfma_f32_32x32x16_bf16 v[0:15], v[48:51], v[52:55], v[0:15]
	s_waitcnt lgkmcnt(4)
	v_mfma_f32_32x32x16_bf16 v[0:15], v[56:59], v[60:63], v[0:15]
	s_waitcnt lgkmcnt(2)
	v_mfma_f32_32x32x16_bf16 v[0:15], v[64:67], v[68:71], v[0:15]
	s_waitcnt lgkmcnt(0)
	v_mfma_f32_32x32x16_bf16 v[0:15], v[72:75], v[76:79], v[0:15]
	ds_read2st64_b32 v[80:81], v86 offset1:1
	ds_read_b128 v[16:19], v87
	ds_read_b128 v[20:23], v87 offset:32
	ds_read_b128 v[24:27], v87 offset:64
	ds_read_b128 v[28:31], v87 offset:96
	ds_read_b128 v[32:35], v87 offset:256
	ds_read_b128 v[36:39], v87 offset:288
	ds_read_b128 v[40:43], v87 offset:320
	ds_read_b128 v[44:47], v87 offset:352
	s_cmp_ge_u32 s87, 0x100
	s_cbranch_scc1 .Lk3_q
	ds_read_b128 v[48:51], v87 offset:512
	ds_read_b128 v[52:55], v87 offset:544
	ds_read_b128 v[56:59], v87 offset:576
	ds_read_b128 v[60:63], v87 offset:608
	ds_read_b128 v[64:67], v87 offset:768
	ds_read_b128 v[68:71], v87 offset:800
	s_waitcnt lgkmcnt(14)
	ds_read_b128 v[72:75], v87 offset:832
	s_waitcnt lgkmcnt(14)
	ds_read_b128 v[76:79], v87 offset:864
	s_mul_i32 s3, s1, 0x2200
	v_mul_u32_u24_e32 v97, 0x440, v189
	v_add_u32_e32 v97, s3, v97
	v_lshl_add_u32 v97, v83, 2, v97
	v_add_u32_e32 v97, 0x11800, v97
	v_sub_u32_e32 v98, 0x29b3c, v97
	s_waitcnt lgkmcnt(3)
	v_sub_f32_e32 v89, v16, v80
	v_sub_f32_e32 v90, v32, v81
	v_min_f32_e32 v89, 0, v89
	v_min_f32_e32 v90, 0, v90
	v_mul_f32_e32 v89, 0x3fb8aa3b, v89
	v_mul_f32_e32 v90, 0x3fb8aa3b, v90
	v_exp_f32_e32 v89, v89
	v_exp_f32_e32 v90, v90
	v_mul_f32_e32 v91, v48, v0
	v_mul_f32_e32 v92, v64, v0
	v_cmp_gt_i32_e32 vcc, 0, v99
	v_cmp_lt_i32_e64 s[42:43], 0, v99
	v_mul_f32_e32 v91, v89, v91
	v_mul_f32_e32 v92, v90, v92
	v_cndmask_b32_e32 v91, 0, v91, vcc
	v_cndmask_b32_e64 v92, 0, v92, s[42:43]
	ds_write_b32 v97, v91
	ds_write_b32 v98, v92 offset:7344
	v_sub_f32_e32 v93, v17, v80
	v_sub_f32_e32 v94, v33, v81
	v_min_f32_e32 v93, 0, v93
	v_min_f32_e32 v94, 0, v94
	v_mul_f32_e32 v93, 0x3fb8aa3b, v93
	v_mul_f32_e32 v94, 0x3fb8aa3b, v94
	v_exp_f32_e32 v93, v93
	v_exp_f32_e32 v94, v94
	v_mul_f32_e32 v95, v49, v1
	v_mul_f32_e32 v96, v65, v1
	v_cmp_gt_i32_e32 vcc, 1, v99
	v_cmp_lt_i32_e64 s[42:43], 1, v99
	v_mul_f32_e32 v95, v93, v95
	v_mul_f32_e32 v96, v94, v96
	v_cndmask_b32_e32 v95, 0, v95, vcc
	v_cndmask_b32_e64 v96, 0, v96, s[42:43]
	ds_write_b32 v97, v95 offset:272
	ds_write_b32 v98, v96 offset:7072
	v_sub_f32_e32 v89, v18, v80
	v_sub_f32_e32 v90, v34, v81
	v_min_f32_e32 v89, 0, v89
	v_min_f32_e32 v90, 0, v90
	v_mul_f32_e32 v89, 0x3fb8aa3b, v89
	v_mul_f32_e32 v90, 0x3fb8aa3b, v90
	v_exp_f32_e32 v89, v89
	v_exp_f32_e32 v90, v90
	v_mul_f32_e32 v91, v50, v2
	v_mul_f32_e32 v92, v66, v2
	v_cmp_gt_i32_e32 vcc, 2, v99
	v_cmp_lt_i32_e64 s[42:43], 2, v99
	v_mul_f32_e32 v91, v89, v91
	v_mul_f32_e32 v92, v90, v92
	v_cndmask_b32_e32 v91, 0, v91, vcc
	v_cndmask_b32_e64 v92, 0, v92, s[42:43]
	ds_write_b32 v97, v91 offset:544
	ds_write_b32 v98, v92 offset:6800
	v_sub_f32_e32 v93, v19, v80
	v_sub_f32_e32 v94, v35, v81
	v_min_f32_e32 v93, 0, v93
	v_min_f32_e32 v94, 0, v94
	v_mul_f32_e32 v93, 0x3fb8aa3b, v93
	v_mul_f32_e32 v94, 0x3fb8aa3b, v94
	v_exp_f32_e32 v93, v93
	v_exp_f32_e32 v94, v94
	v_mul_f32_e32 v95, v51, v3
	v_mul_f32_e32 v96, v67, v3
	v_cmp_gt_i32_e32 vcc, 3, v99
	v_cmp_lt_i32_e64 s[42:43], 3, v99
	v_mul_f32_e32 v95, v93, v95
	v_mul_f32_e32 v96, v94, v96
	v_cndmask_b32_e32 v95, 0, v95, vcc
	v_cndmask_b32_e64 v96, 0, v96, s[42:43]
	ds_write_b32 v97, v95 offset:816
	ds_write_b32 v98, v96 offset:6528
	s_waitcnt lgkmcnt(2)
	v_sub_f32_e32 v89, v20, v80
	v_sub_f32_e32 v90, v36, v81
	v_min_f32_e32 v89, 0, v89
	v_min_f32_e32 v90, 0, v90
	v_mul_f32_e32 v89, 0x3fb8aa3b, v89
	v_mul_f32_e32 v90, 0x3fb8aa3b, v90
	v_exp_f32_e32 v89, v89
	v_exp_f32_e32 v90, v90
	v_mul_f32_e32 v91, v52, v4
	v_mul_f32_e32 v92, v68, v4
	v_cmp_gt_i32_e32 vcc, 8, v99
	v_cmp_lt_i32_e64 s[42:43], 8, v99
	v_mul_f32_e32 v91, v89, v91
	v_mul_f32_e32 v92, v90, v92
	v_cndmask_b32_e32 v91, 0, v91, vcc
	v_cndmask_b32_e64 v92, 0, v92, s[42:43]
	ds_write_b32 v97, v91 offset:2176
	ds_write_b32 v98, v92 offset:5168
	v_sub_f32_e32 v93, v21, v80
	v_sub_f32_e32 v94, v37, v81
	v_min_f32_e32 v93, 0, v93
	v_min_f32_e32 v94, 0, v94
	v_mul_f32_e32 v93, 0x3fb8aa3b, v93
	v_mul_f32_e32 v94, 0x3fb8aa3b, v94
	v_exp_f32_e32 v93, v93
	v_exp_f32_e32 v94, v94
	v_mul_f32_e32 v95, v53, v5
	v_mul_f32_e32 v96, v69, v5
	v_cmp_gt_i32_e32 vcc, 9, v99
	v_cmp_lt_i32_e64 s[42:43], 9, v99
	v_mul_f32_e32 v95, v93, v95
	v_mul_f32_e32 v96, v94, v96
	v_cndmask_b32_e32 v95, 0, v95, vcc
	v_cndmask_b32_e64 v96, 0, v96, s[42:43]
	ds_write_b32 v97, v95 offset:2448
	ds_write_b32 v98, v96 offset:4896
	v_sub_f32_e32 v89, v22, v80
	v_sub_f32_e32 v90, v38, v81
	v_min_f32_e32 v89, 0, v89
	v_min_f32_e32 v90, 0, v90
	v_mul_f32_e32 v89, 0x3fb8aa3b, v89
	v_mul_f32_e32 v90, 0x3fb8aa3b, v90
	v_exp_f32_e32 v89, v89
	v_exp_f32_e32 v90, v90
	v_mul_f32_e32 v91, v54, v6
	v_mul_f32_e32 v92, v70, v6
	v_cmp_gt_i32_e32 vcc, 10, v99
	v_cmp_lt_i32_e64 s[42:43], 10, v99
	v_mul_f32_e32 v91, v89, v91
	v_mul_f32_e32 v92, v90, v92
	v_cndmask_b32_e32 v91, 0, v91, vcc
	v_cndmask_b32_e64 v92, 0, v92, s[42:43]
	ds_write_b32 v97, v91 offset:2720
	ds_write_b32 v98, v92 offset:4624
	v_sub_f32_e32 v93, v23, v80
	v_sub_f32_e32 v94, v39, v81
	v_min_f32_e32 v93, 0, v93
	v_min_f32_e32 v94, 0, v94
	v_mul_f32_e32 v93, 0x3fb8aa3b, v93
	v_mul_f32_e32 v94, 0x3fb8aa3b, v94
	v_exp_f32_e32 v93, v93
	v_exp_f32_e32 v94, v94
	v_mul_f32_e32 v95, v55, v7
	v_mul_f32_e32 v96, v71, v7
	v_cmp_gt_i32_e32 vcc, 11, v99
	v_cmp_lt_i32_e64 s[42:43], 11, v99
	v_mul_f32_e32 v95, v93, v95
	v_mul_f32_e32 v96, v94, v96
	v_cndmask_b32_e32 v95, 0, v95, vcc
	v_cndmask_b32_e64 v96, 0, v96, s[42:43]
	ds_write_b32 v97, v95 offset:2992
	ds_write_b32 v98, v96 offset:4352
	s_waitcnt lgkmcnt(1)
	v_sub_f32_e32 v89, v24, v80
	v_sub_f32_e32 v90, v40, v81
	v_min_f32_e32 v89, 0, v89
	v_min_f32_e32 v90, 0, v90
	v_mul_f32_e32 v89, 0x3fb8aa3b, v89
	v_mul_f32_e32 v90, 0x3fb8aa3b, v90
	v_exp_f32_e32 v89, v89
	v_exp_f32_e32 v90, v90
	v_mul_f32_e32 v91, v56, v8
	v_mul_f32_e32 v92, v72, v8
	v_cmp_gt_i32_e32 vcc, 16, v99
	v_cmp_lt_i32_e64 s[42:43], 16, v99
	v_mul_f32_e32 v91, v89, v91
	v_mul_f32_e32 v92, v90, v92
	v_cndmask_b32_e32 v91, 0, v91, vcc
	v_cndmask_b32_e64 v92, 0, v92, s[42:43]
	ds_write_b32 v97, v91 offset:4352
	ds_write_b32 v98, v92 offset:2992
	v_sub_f32_e32 v93, v25, v80
	v_sub_f32_e32 v94, v41, v81
	v_min_f32_e32 v93, 0, v93
	v_min_f32_e32 v94, 0, v94
	v_mul_f32_e32 v93, 0x3fb8aa3b, v93
	v_mul_f32_e32 v94, 0x3fb8aa3b, v94
	v_exp_f32_e32 v93, v93
	v_exp_f32_e32 v94, v94
	v_mul_f32_e32 v95, v57, v9
	v_mul_f32_e32 v96, v73, v9
	v_cmp_gt_i32_e32 vcc, 17, v99
	v_cmp_lt_i32_e64 s[42:43], 17, v99
	v_mul_f32_e32 v95, v93, v95
	v_mul_f32_e32 v96, v94, v96
	v_cndmask_b32_e32 v95, 0, v95, vcc
	v_cndmask_b32_e64 v96, 0, v96, s[42:43]
	ds_write_b32 v97, v95 offset:4624
	ds_write_b32 v98, v96 offset:2720
	v_sub_f32_e32 v89, v26, v80
	v_sub_f32_e32 v90, v42, v81
	v_min_f32_e32 v89, 0, v89
	v_min_f32_e32 v90, 0, v90
	v_mul_f32_e32 v89, 0x3fb8aa3b, v89
	v_mul_f32_e32 v90, 0x3fb8aa3b, v90
	v_exp_f32_e32 v89, v89
	v_exp_f32_e32 v90, v90
	v_mul_f32_e32 v91, v58, v10
	v_mul_f32_e32 v92, v74, v10
	v_cmp_gt_i32_e32 vcc, 18, v99
	v_cmp_lt_i32_e64 s[42:43], 18, v99
	v_mul_f32_e32 v91, v89, v91
	v_mul_f32_e32 v92, v90, v92
	v_cndmask_b32_e32 v91, 0, v91, vcc
	v_cndmask_b32_e64 v92, 0, v92, s[42:43]
	ds_write_b32 v97, v91 offset:4896
	ds_write_b32 v98, v92 offset:2448
	v_sub_f32_e32 v93, v27, v80
	v_sub_f32_e32 v94, v43, v81
	v_min_f32_e32 v93, 0, v93
	v_min_f32_e32 v94, 0, v94
	v_mul_f32_e32 v93, 0x3fb8aa3b, v93
	v_mul_f32_e32 v94, 0x3fb8aa3b, v94
	v_exp_f32_e32 v93, v93
	v_exp_f32_e32 v94, v94
	v_mul_f32_e32 v95, v59, v11
	v_mul_f32_e32 v96, v75, v11
	v_cmp_gt_i32_e32 vcc, 19, v99
	v_cmp_lt_i32_e64 s[42:43], 19, v99
	v_mul_f32_e32 v95, v93, v95
	v_mul_f32_e32 v96, v94, v96
	v_cndmask_b32_e32 v95, 0, v95, vcc
	v_cndmask_b32_e64 v96, 0, v96, s[42:43]
	ds_write_b32 v97, v95 offset:5168
	ds_write_b32 v98, v96 offset:2176
	s_waitcnt lgkmcnt(0)
	v_sub_f32_e32 v89, v28, v80
	v_sub_f32_e32 v90, v44, v81
	v_min_f32_e32 v89, 0, v89
	v_min_f32_e32 v90, 0, v90
	v_mul_f32_e32 v89, 0x3fb8aa3b, v89
	v_mul_f32_e32 v90, 0x3fb8aa3b, v90
	v_exp_f32_e32 v89, v89
	v_exp_f32_e32 v90, v90
	v_mul_f32_e32 v91, v60, v12
	v_mul_f32_e32 v92, v76, v12
	v_cmp_gt_i32_e32 vcc, 24, v99
	v_cmp_lt_i32_e64 s[42:43], 24, v99
	v_mul_f32_e32 v91, v89, v91
	v_mul_f32_e32 v92, v90, v92
	v_cndmask_b32_e32 v91, 0, v91, vcc
	v_cndmask_b32_e64 v92, 0, v92, s[42:43]
	ds_write_b32 v97, v91 offset:6528
	ds_write_b32 v98, v92 offset:816
	v_sub_f32_e32 v93, v29, v80
	v_sub_f32_e32 v94, v45, v81
	v_min_f32_e32 v93, 0, v93
	v_min_f32_e32 v94, 0, v94
	v_mul_f32_e32 v93, 0x3fb8aa3b, v93
	v_mul_f32_e32 v94, 0x3fb8aa3b, v94
	v_exp_f32_e32 v93, v93
	v_exp_f32_e32 v94, v94
	v_mul_f32_e32 v95, v61, v13
	v_mul_f32_e32 v96, v77, v13
	v_cmp_gt_i32_e32 vcc, 25, v99
	v_cmp_lt_i32_e64 s[42:43], 25, v99
	v_mul_f32_e32 v95, v93, v95
	v_mul_f32_e32 v96, v94, v96
	v_cndmask_b32_e32 v95, 0, v95, vcc
	v_cndmask_b32_e64 v96, 0, v96, s[42:43]
	ds_write_b32 v97, v95 offset:6800
	ds_write_b32 v98, v96 offset:544
	v_sub_f32_e32 v89, v30, v80
	v_sub_f32_e32 v90, v46, v81
	v_min_f32_e32 v89, 0, v89
	v_min_f32_e32 v90, 0, v90
	v_mul_f32_e32 v89, 0x3fb8aa3b, v89
	v_mul_f32_e32 v90, 0x3fb8aa3b, v90
	v_exp_f32_e32 v89, v89
	v_exp_f32_e32 v90, v90
	v_mul_f32_e32 v91, v62, v14
	v_mul_f32_e32 v92, v78, v14
	v_cmp_gt_i32_e32 vcc, 26, v99
	v_cmp_lt_i32_e64 s[42:43], 26, v99
	v_mul_f32_e32 v91, v89, v91
	v_mul_f32_e32 v92, v90, v92
	v_cndmask_b32_e32 v91, 0, v91, vcc
	v_cndmask_b32_e64 v92, 0, v92, s[42:43]
	ds_write_b32 v97, v91 offset:7072
	ds_write_b32 v98, v92 offset:272
	v_sub_f32_e32 v93, v31, v80
	v_sub_f32_e32 v94, v47, v81
	v_min_f32_e32 v93, 0, v93
	v_min_f32_e32 v94, 0, v94
	v_mul_f32_e32 v93, 0x3fb8aa3b, v93
	v_mul_f32_e32 v94, 0x3fb8aa3b, v94
	v_exp_f32_e32 v93, v93
	v_exp_f32_e32 v94, v94
	v_mul_f32_e32 v95, v63, v15
	v_mul_f32_e32 v96, v79, v15
	v_cmp_gt_i32_e32 vcc, 27, v99
	v_cmp_lt_i32_e64 s[42:43], 27, v99
	v_mul_f32_e32 v95, v93, v95
	v_mul_f32_e32 v96, v94, v96
	v_cndmask_b32_e32 v95, 0, v95, vcc
	v_cndmask_b32_e64 v96, 0, v96, s[42:43]
	ds_write_b32 v97, v95 offset:7344
	ds_write_b32 v98, v96
	s_branch .Lk3_done
.Lk3_q:
	s_mul_i32 s3, s1, 0x1200
	v_mul_u32_u24_e32 v97, 0x240, v189
	v_add_u32_e32 v97, s3, v97
	v_lshl_add_u32 v97, v83, 1, v97
	v_add_u32_e32 v97, 0x1a000, v97
	s_waitcnt lgkmcnt(0)
	v_sub_f32_e32 v89, v16, v80
	v_sub_f32_e32 v90, v32, v81
	v_min_f32_e32 v89, 0, v89
	v_min_f32_e32 v90, 0, v90
	v_mul_f32_e32 v89, 0x3fb8aa3b, v89
	v_mul_f32_e32 v90, 0x3fb8aa3b, v90
	v_exp_f32_e32 v89, v89
	v_exp_f32_e32 v90, v90
	v_mul_f32_e32 v91, v89, v0
	v_mul_f32_e32 v92, v90, v0
	v_cmp_ge_i32_e32 vcc, 0, v99
	v_cmp_le_i32_e64 s[42:43], 0, v99
	v_cvt_pk_bf16_f32 v91, v91, v91
	v_cvt_pk_bf16_f32 v92, v92, v92
	v_cndmask_b32_e32 v91, 0, v91, vcc
	v_cndmask_b32_e64 v92, 0, v92, s[42:43]
	ds_write_b16 v97, v91
	ds_write_b16 v97, v92 offset:9216
	v_sub_f32_e32 v93, v17, v80
	v_sub_f32_e32 v94, v33, v81
	v_min_f32_e32 v93, 0, v93
	v_min_f32_e32 v94, 0, v94
	v_mul_f32_e32 v93, 0x3fb8aa3b, v93
	v_mul_f32_e32 v94, 0x3fb8aa3b, v94
	v_exp_f32_e32 v93, v93
	v_exp_f32_e32 v94, v94
	v_mul_f32_e32 v95, v93, v1
	v_mul_f32_e32 v96, v94, v1
	v_cmp_ge_i32_e32 vcc, 1, v99
	v_cmp_le_i32_e64 s[42:43], 1, v99
	v_cvt_pk_bf16_f32 v95, v95, v95
	v_cvt_pk_bf16_f32 v96, v96, v96
	v_cndmask_b32_e32 v95, 0, v95, vcc
	v_cndmask_b32_e64 v96, 0, v96, s[42:43]
	ds_write_b16 v97, v95 offset:144
	ds_write_b16 v97, v96 offset:9360
	v_sub_f32_e32 v89, v18, v80
	v_sub_f32_e32 v90, v34, v81
	v_min_f32_e32 v89, 0, v89
	v_min_f32_e32 v90, 0, v90
	v_mul_f32_e32 v89, 0x3fb8aa3b, v89
	v_mul_f32_e32 v90, 0x3fb8aa3b, v90
	v_exp_f32_e32 v89, v89
	v_exp_f32_e32 v90, v90
	v_mul_f32_e32 v91, v89, v2
	v_mul_f32_e32 v92, v90, v2
	v_cmp_ge_i32_e32 vcc, 2, v99
	v_cmp_le_i32_e64 s[42:43], 2, v99
	v_cvt_pk_bf16_f32 v91, v91, v91
	v_cvt_pk_bf16_f32 v92, v92, v92
	v_cndmask_b32_e32 v91, 0, v91, vcc
	v_cndmask_b32_e64 v92, 0, v92, s[42:43]
	ds_write_b16 v97, v91 offset:288
	ds_write_b16 v97, v92 offset:9504
	v_sub_f32_e32 v93, v19, v80
	v_sub_f32_e32 v94, v35, v81
	v_min_f32_e32 v93, 0, v93
	v_min_f32_e32 v94, 0, v94
	v_mul_f32_e32 v93, 0x3fb8aa3b, v93
	v_mul_f32_e32 v94, 0x3fb8aa3b, v94
	v_exp_f32_e32 v93, v93
	v_exp_f32_e32 v94, v94
	v_mul_f32_e32 v95, v93, v3
	v_mul_f32_e32 v96, v94, v3
	v_cmp_ge_i32_e32 vcc, 3, v99
	v_cmp_le_i32_e64 s[42:43], 3, v99
	v_cvt_pk_bf16_f32 v95, v95, v95
	v_cvt_pk_bf16_f32 v96, v96, v96
	v_cndmask_b32_e32 v95, 0, v95, vcc
	v_cndmask_b32_e64 v96, 0, v96, s[42:43]
	ds_write_b16 v97, v95 offset:432
	ds_write_b16 v97, v96 offset:9648
	v_sub_f32_e32 v89, v20, v80
	v_sub_f32_e32 v90, v36, v81
	v_min_f32_e32 v89, 0, v89
	v_min_f32_e32 v90, 0, v90
	v_mul_f32_e32 v89, 0x3fb8aa3b, v89
	v_mul_f32_e32 v90, 0x3fb8aa3b, v90
	v_exp_f32_e32 v89, v89
	v_exp_f32_e32 v90, v90
	v_mul_f32_e32 v91, v89, v4
	v_mul_f32_e32 v92, v90, v4
	v_cmp_ge_i32_e32 vcc, 8, v99
	v_cmp_le_i32_e64 s[42:43], 8, v99
	v_cvt_pk_bf16_f32 v91, v91, v91
	v_cvt_pk_bf16_f32 v92, v92, v92
	v_cndmask_b32_e32 v91, 0, v91, vcc
	v_cndmask_b32_e64 v92, 0, v92, s[42:43]
	ds_write_b16 v97, v91 offset:1152
	ds_write_b16 v97, v92 offset:10368
	v_sub_f32_e32 v93, v21, v80
	v_sub_f32_e32 v94, v37, v81
	v_min_f32_e32 v93, 0, v93
	v_min_f32_e32 v94, 0, v94
	v_mul_f32_e32 v93, 0x3fb8aa3b, v93
	v_mul_f32_e32 v94, 0x3fb8aa3b, v94
	v_exp_f32_e32 v93, v93
	v_exp_f32_e32 v94, v94
	v_mul_f32_e32 v95, v93, v5
	v_mul_f32_e32 v96, v94, v5
	v_cmp_ge_i32_e32 vcc, 9, v99
	v_cmp_le_i32_e64 s[42:43], 9, v99
	v_cvt_pk_bf16_f32 v95, v95, v95
	v_cvt_pk_bf16_f32 v96, v96, v96
	v_cndmask_b32_e32 v95, 0, v95, vcc
	v_cndmask_b32_e64 v96, 0, v96, s[42:43]
	ds_write_b16 v97, v95 offset:1296
	ds_write_b16 v97, v96 offset:10512
	v_sub_f32_e32 v89, v22, v80
	v_sub_f32_e32 v90, v38, v81
	v_min_f32_e32 v89, 0, v89
	v_min_f32_e32 v90, 0, v90
	v_mul_f32_e32 v89, 0x3fb8aa3b, v89
	v_mul_f32_e32 v90, 0x3fb8aa3b, v90
	v_exp_f32_e32 v89, v89
	v_exp_f32_e32 v90, v90
	v_mul_f32_e32 v91, v89, v6
	v_mul_f32_e32 v92, v90, v6
	v_cmp_ge_i32_e32 vcc, 10, v99
	v_cmp_le_i32_e64 s[42:43], 10, v99
	v_cvt_pk_bf16_f32 v91, v91, v91
	v_cvt_pk_bf16_f32 v92, v92, v92
	v_cndmask_b32_e32 v91, 0, v91, vcc
	v_cndmask_b32_e64 v92, 0, v92, s[42:43]
	ds_write_b16 v97, v91 offset:1440
	ds_write_b16 v97, v92 offset:10656
	v_sub_f32_e32 v93, v23, v80
	v_sub_f32_e32 v94, v39, v81
	v_min_f32_e32 v93, 0, v93
	v_min_f32_e32 v94, 0, v94
	v_mul_f32_e32 v93, 0x3fb8aa3b, v93
	v_mul_f32_e32 v94, 0x3fb8aa3b, v94
	v_exp_f32_e32 v93, v93
	v_exp_f32_e32 v94, v94
	v_mul_f32_e32 v95, v93, v7
	v_mul_f32_e32 v96, v94, v7
	v_cmp_ge_i32_e32 vcc, 11, v99
	v_cmp_le_i32_e64 s[42:43], 11, v99
	v_cvt_pk_bf16_f32 v95, v95, v95
	v_cvt_pk_bf16_f32 v96, v96, v96
	v_cndmask_b32_e32 v95, 0, v95, vcc
	v_cndmask_b32_e64 v96, 0, v96, s[42:43]
	ds_write_b16 v97, v95 offset:1584
	ds_write_b16 v97, v96 offset:10800
	v_sub_f32_e32 v89, v24, v80
	v_sub_f32_e32 v90, v40, v81
	v_min_f32_e32 v89, 0, v89
	v_min_f32_e32 v90, 0, v90
	v_mul_f32_e32 v89, 0x3fb8aa3b, v89
	v_mul_f32_e32 v90, 0x3fb8aa3b, v90
	v_exp_f32_e32 v89, v89
	v_exp_f32_e32 v90, v90
	v_mul_f32_e32 v91, v89, v8
	v_mul_f32_e32 v92, v90, v8
	v_cmp_ge_i32_e32 vcc, 16, v99
	v_cmp_le_i32_e64 s[42:43], 16, v99
	v_cvt_pk_bf16_f32 v91, v91, v91
	v_cvt_pk_bf16_f32 v92, v92, v92
	v_cndmask_b32_e32 v91, 0, v91, vcc
	v_cndmask_b32_e64 v92, 0, v92, s[42:43]
	ds_write_b16 v97, v91 offset:2304
	ds_write_b16 v97, v92 offset:11520
	v_sub_f32_e32 v93, v25, v80
	v_sub_f32_e32 v94, v41, v81
	v_min_f32_e32 v93, 0, v93
	v_min_f32_e32 v94, 0, v94
	v_mul_f32_e32 v93, 0x3fb8aa3b, v93
	v_mul_f32_e32 v94, 0x3fb8aa3b, v94
	v_exp_f32_e32 v93, v93
	v_exp_f32_e32 v94, v94
	v_mul_f32_e32 v95, v93, v9
	v_mul_f32_e32 v96, v94, v9
	v_cmp_ge_i32_e32 vcc, 17, v99
	v_cmp_le_i32_e64 s[42:43], 17, v99
	v_cvt_pk_bf16_f32 v95, v95, v95
	v_cvt_pk_bf16_f32 v96, v96, v96
	v_cndmask_b32_e32 v95, 0, v95, vcc
	v_cndmask_b32_e64 v96, 0, v96, s[42:43]
	ds_write_b16 v97, v95 offset:2448
	ds_write_b16 v97, v96 offset:11664
	v_sub_f32_e32 v89, v26, v80
	v_sub_f32_e32 v90, v42, v81
	v_min_f32_e32 v89, 0, v89
	v_min_f32_e32 v90, 0, v90
	v_mul_f32_e32 v89, 0x3fb8aa3b, v89
	v_mul_f32_e32 v90, 0x3fb8aa3b, v90
	v_exp_f32_e32 v89, v89
	v_exp_f32_e32 v90, v90
	v_mul_f32_e32 v91, v89, v10
	v_mul_f32_e32 v92, v90, v10
	v_cmp_ge_i32_e32 vcc, 18, v99
	v_cmp_le_i32_e64 s[42:43], 18, v99
	v_cvt_pk_bf16_f32 v91, v91, v91
	v_cvt_pk_bf16_f32 v92, v92, v92
	v_cndmask_b32_e32 v91, 0, v91, vcc
	v_cndmask_b32_e64 v92, 0, v92, s[42:43]
	ds_write_b16 v97, v91 offset:2592
	ds_write_b16 v97, v92 offset:11808
	v_sub_f32_e32 v93, v27, v80
	v_sub_f32_e32 v94, v43, v81
	v_min_f32_e32 v93, 0, v93
	v_min_f32_e32 v94, 0, v94
	v_mul_f32_e32 v93, 0x3fb8aa3b, v93
	v_mul_f32_e32 v94, 0x3fb8aa3b, v94
	v_exp_f32_e32 v93, v93
	v_exp_f32_e32 v94, v94
	v_mul_f32_e32 v95, v93, v11
	v_mul_f32_e32 v96, v94, v11
	v_cmp_ge_i32_e32 vcc, 19, v99
	v_cmp_le_i32_e64 s[42:43], 19, v99
	v_cvt_pk_bf16_f32 v95, v95, v95
	v_cvt_pk_bf16_f32 v96, v96, v96
	v_cndmask_b32_e32 v95, 0, v95, vcc
	v_cndmask_b32_e64 v96, 0, v96, s[42:43]
	ds_write_b16 v97, v95 offset:2736
	ds_write_b16 v97, v96 offset:11952
	v_sub_f32_e32 v89, v28, v80
	v_sub_f32_e32 v90, v44, v81
	v_min_f32_e32 v89, 0, v89
	v_min_f32_e32 v90, 0, v90
	v_mul_f32_e32 v89, 0x3fb8aa3b, v89
	v_mul_f32_e32 v90, 0x3fb8aa3b, v90
	v_exp_f32_e32 v89, v89
	v_exp_f32_e32 v90, v90
	v_mul_f32_e32 v91, v89, v12
	v_mul_f32_e32 v92, v90, v12
	v_cmp_ge_i32_e32 vcc, 24, v99
	v_cmp_le_i32_e64 s[42:43], 24, v99
	v_cvt_pk_bf16_f32 v91, v91, v91
	v_cvt_pk_bf16_f32 v92, v92, v92
	v_cndmask_b32_e32 v91, 0, v91, vcc
	v_cndmask_b32_e64 v92, 0, v92, s[42:43]
	ds_write_b16 v97, v91 offset:3456
	ds_write_b16 v97, v92 offset:12672
	v_sub_f32_e32 v93, v29, v80
	v_sub_f32_e32 v94, v45, v81
	v_min_f32_e32 v93, 0, v93
	v_min_f32_e32 v94, 0, v94
	v_mul_f32_e32 v93, 0x3fb8aa3b, v93
	v_mul_f32_e32 v94, 0x3fb8aa3b, v94
	v_exp_f32_e32 v93, v93
	v_exp_f32_e32 v94, v94
	v_mul_f32_e32 v95, v93, v13
	v_mul_f32_e32 v96, v94, v13
	v_cmp_ge_i32_e32 vcc, 25, v99
	v_cmp_le_i32_e64 s[42:43], 25, v99
	v_cvt_pk_bf16_f32 v95, v95, v95
	v_cvt_pk_bf16_f32 v96, v96, v96
	v_cndmask_b32_e32 v95, 0, v95, vcc
	v_cndmask_b32_e64 v96, 0, v96, s[42:43]
	ds_write_b16 v97, v95 offset:3600
	ds_write_b16 v97, v96 offset:12816
	v_sub_f32_e32 v89, v30, v80
	v_sub_f32_e32 v90, v46, v81
	v_min_f32_e32 v89, 0, v89
	v_min_f32_e32 v90, 0, v90
	v_mul_f32_e32 v89, 0x3fb8aa3b, v89
	v_mul_f32_e32 v90, 0x3fb8aa3b, v90
	v_exp_f32_e32 v89, v89
	v_exp_f32_e32 v90, v90
	v_mul_f32_e32 v91, v89, v14
	v_mul_f32_e32 v92, v90, v14
	v_cmp_ge_i32_e32 vcc, 26, v99
	v_cmp_le_i32_e64 s[42:43], 26, v99
	v_cvt_pk_bf16_f32 v91, v91, v91
	v_cvt_pk_bf16_f32 v92, v92, v92
	v_cndmask_b32_e32 v91, 0, v91, vcc
	v_cndmask_b32_e64 v92, 0, v92, s[42:43]
	ds_write_b16 v97, v91 offset:3744
	ds_write_b16 v97, v92 offset:12960
	v_sub_f32_e32 v93, v31, v80
	v_sub_f32_e32 v94, v47, v81
	v_min_f32_e32 v93, 0, v93
	v_min_f32_e32 v94, 0, v94
	v_mul_f32_e32 v93, 0x3fb8aa3b, v93
	v_mul_f32_e32 v94, 0x3fb8aa3b, v94
	v_exp_f32_e32 v93, v93
	v_exp_f32_e32 v94, v94
	v_mul_f32_e32 v95, v93, v15
	v_mul_f32_e32 v96, v94, v15
	v_cmp_ge_i32_e32 vcc, 27, v99
	v_cmp_le_i32_e64 s[42:43], 27, v99
	v_cvt_pk_bf16_f32 v95, v95, v95
	v_cvt_pk_bf16_f32 v96, v96, v96
	v_cndmask_b32_e32 v95, 0, v95, vcc
	v_cndmask_b32_e64 v96, 0, v96, s[42:43]
	ds_write_b16 v97, v95 offset:3888
	ds_write_b16 v97, v96 offset:13104
.Lk3_done:
	s_mul_hi_i32 s5, s15, 0x12000
	s_mul_i32 s4, s15, 0x12000
	v_cmp_lt_i32_e32 vcc, 1, v82
	v_lshlrev_b32_e32 v128, 1, v215
	s_waitcnt lgkmcnt(0)
	s_barrier
	s_and_saveexec_b64 s[0:1], vcc
	s_xor_b64 s[2:3], exec, s[0:1]
	s_cbranch_execz .LBB0_282
	s_add_i32 s0, s28, s86
	s_cmpk_lt_i32 s0, 0x900
	s_cselect_b32 s0, s0, s28
	s_mul_hi_i32 s1, s0, 0x2aaaaaab
	s_lshr_b32 s6, s1, 31
	s_ashr_i32 s1, s1, 1
	s_add_i32 s1, s1, s6
	s_mul_i32 s6, s1, -12
	s_add_i32 s6, s6, s0
	v_lshl_add_u32 v3, s1, 6, v187
	v_readlane_b32 s0, v253, 59
	v_readlane_b32 s1, v253, 60
	s_lshl_b32 s10, s6, 7
	s_ashr_i32 s11, s10, 31
	v_mov_b64_e32 v[0:1], s[0:1]
	s_movk_i32 s0, 0x3800
	v_mad_i64_i32 v[0:1], s[0:1], v3, s0, v[0:1]
	v_lshl_add_u64 v[0:1], s[10:11], 1, v[0:1]
	v_lshl_add_u64 v[0:1], v[0:1], 0, v[128:129]
	global_load_dwordx4 v[96:99], v[0:1], off offset:2064
	global_load_dwordx4 v[72:75], v[0:1], off offset:2048
	v_cmp_gt_i32_e32 vcc, s85, v3
	v_mov_b32_e32 v86, v129
	v_mov_b32_e32 v87, v129
	v_cndmask_b32_e32 v2, v240, v241, vcc
	v_and_b32_e32 v3, v2, v3
	s_mov_b64 s[0:1], 0x800
	v_mov_b32_e32 v84, v129
	v_mov_b32_e32 v85, v129
	v_mov_b64_e32 v[90:91], v[86:87]
	v_mov_b64_e32 v[106:107], v[86:87]
	v_cmp_ne_u32_e64 s[42:43], 0, v3
	v_lshl_add_u64 v[0:1], v[0:1], 0, s[0:1]
	v_mov_b64_e32 v[88:89], v[84:85]
	v_mov_b64_e32 v[104:105], v[84:85]
	s_and_saveexec_b64 s[16:17], s[42:43]
	s_cbranch_execz .LBB0_261
	s_movk_i32 s0, 0xc800
	v_add_co_u32_e32 v6, vcc, 0xffffd000, v0
	s_mov_b32 s1, -1
	s_nop 0
	v_addc_co_u32_e32 v7, vcc, -1, v1, vcc
	v_lshl_add_u64 v[4:5], v[0:1], 0, s[0:1]
	global_load_dwordx4 v[88:91], v[6:7], off offset:-2048
	global_load_dwordx4 v[104:107], v[4:5], off offset:16
